# P5 combine: touch-prefetch of the lines the iteration two steps ahead reads (next batch, same frequency row), loop waits vmcnt(6)
# baseline (speedup 1.0000x reference)
; __device__ __forceinline__ int obid() { int b = (int)blockIdx.x; asm volatile("" : "+s"(b)); return b; }
; __device__ __forceinline__ int otid() { int t; asm volatile("v_mov_b32 %0, %1" : "=v"(t) : "v"(threadIdx.x)); return t; }
; __device__ __forceinline__ float bf2f(bf16 b) { return __uint_as_float((unsigned)b << 16); }
; __device__ __forceinline__ void ph_combine(const Params& p_) {
;     ...
;     for (int e0 = obid() * NTHR + otid(); e0 < MTOK * DG / 4; e0 += 2 * nth) {
;         f32x4 ce[2], so[2]; u32x2 gz[2]; float pv[2][4]; int rowv[2], c4v[2], kv[2]; bool use_so[2], act[2];
; #pragma unroll
;         for (int u = 0; u < 2; ++u) { const int e = e0 + u * nth; act[u] = e < MTOK * DG / 4; const int ee = act[u] ? e : e0;
;             const int row = ee >> 7, c4 = (ee & 127) * 4, b = row >> 12, k = row & 4095, kk = (k <= 2048) ? k : 4096 - k;
;             rowv[u] = row; c4v[u] = c4; kv[u] = k; use_so[u] = (kk != 0 && kk != 2048);
;             ce[u] = (kk == 2048) ? *(const f32x4*)(Ce + (size_t)(2 * 2304 + 2 * 2048) * 512 + b * 512 + c4) : *(const f32x4*)(Ce + ((size_t)b * 2304 + kk) * 512 + c4);
;             so[u] = *(const f32x4*)(So + ((size_t)b * 2048 + (use_so[u] ? kk : 1)) * 512 + c4);
;             gz[u] = *(const u32x2*)(Z + (size_t)row * DIN + DG + c4);
; #pragma unroll
;             for (int j = 0; j < 4; ++j) pv[u][j] = bf2f(PQ[((size_t)(b * 512 + c4 + j) * 2) * 4096 + 2048]); }
;         asm volatile("" ::: "memory");
; #pragma unroll
;         for (int u = 0; u < 2; ++u) if (act[u]) { f32x4 s = ce[u];
;             if (use_so[u]) s = (kv[u] <= 2048) ? s - so[u] : s + so[u];
.LBB0_664:
	v_ashrrev_i32_e32 v24, 7, v19
	v_and_b32_e32 v0, 0xfff, v24
	s_movk_i32 s3, 0x801
	v_sub_u32_e32 v3, 0x1000, v0
	v_cmp_gt_u32_e64 s[36:37], s3, v0
	v_ashrrev_i32_e32 v2, 19, v19
	v_cmp_ne_u32_e64 s[26:27], 0, v2
	v_and_b32_e32 v22, 0x1fc, v21
	v_cndmask_b32_e64 v6, v3, v0, s[36:37]
	v_cmp_lt_u32_e32 vcc, s68, v0
	v_cmp_ne_u32_e64 s[36:37], s68, v6
	v_lshlrev_b32_e32 v4, 9, v2
	s_and_saveexec_b64 s[12:13], s[36:37]
	s_xor_b64 s[36:37], exec, s[12:13]
	v_mul_i32_i24_e32 v4, 0x900, v2
	v_ashrrev_i32_e32 v5, 31, v4
	v_mov_b32_e32 v7, v1
	v_lshl_add_u64 v[4:5], v[6:7], 0, v[4:5]
	v_lshlrev_b64 v[4:5], 11, v[4:5]
	v_lshl_add_u64 v[4:5], s[50:51], 0, v[4:5]
	v_lshlrev_b32_e32 v0, 2, v22
	v_lshl_add_u64 v[8:9], v[4:5], 0, v[0:1]
	v_lshlrev_b32_e32 v4, 9, v2
	s_andn2_saveexec_b64 s[36:37], s[36:37]
	v_ashrrev_i32_e32 v5, 31, v4
	v_lshl_add_u64 v[8:9], v[4:5], 2, s[60:61]
	v_lshlrev_b32_e32 v0, 2, v22
	v_lshl_add_u64 v[8:9], v[8:9], 0, v[0:1]
	s_or_b64 exec, exec, s[36:37]
	v_and_b32_e32 v0, 0x17ff, v6
	v_ashrrev_i32_e32 v3, 31, v2
	v_lshlrev_b32_e32 v5, 9, v6
	v_cmp_ne_u32_e64 s[42:43], 0, v0
	v_lshlrev_b64 v[2:3], 22, v[2:3]
	v_lshl_add_u64 v[2:3], s[52:53], 0, v[2:3]
	v_cndmask_b32_e64 v0, v196, v5, s[42:43]
	v_lshlrev_b32_e32 v0, 2, v0
	v_lshl_add_u64 v[2:3], v[2:3], 0, v[0:1]
	v_lshlrev_b32_e32 v0, 2, v22
	v_mov_b64_e32 v[6:7], s[48:49]
	v_lshl_add_u64 v[2:3], v[2:3], 0, v[0:1]
	v_mad_i64_i32 v[6:7], s[12:13], v24, s75, v[6:7]
	v_lshlrev_b32_e32 v0, 1, v22
	v_lshl_add_u64 v[6:7], v[6:7], 0, v[0:1]
	s_mov_b32 s3, 0xad20000
	v_add_co_u32_e64 v6, s[36:37], s3, v6
	v_mov_b64_e32 v[40:41], v[8:9]
	global_load_dwordx4 v[10:13], v[8:9], off
	s_nop 0
	v_addc_co_u32_e64 v7, s[36:37], 0, v7, s[36:37]
	v_mov_b64_e32 v[42:43], v[2:3]
	global_load_dwordx4 v[14:17], v[2:3], off
	v_mov_b64_e32 v[44:45], v[6:7]
	global_load_dwordx2 v[28:29], v[6:7], off offset:1024
	v_or_b32_e32 v2, v4, v22
	v_ashrrev_i32_e32 v3, 31, v2
	v_lshlrev_b64 v[4:5], 14, v[2:3]
	v_or_b32_e32 v6, 1, v2
	v_or_b32_e32 v8, 2, v2
	v_or_b32_e32 v2, 3, v2
	v_ashrrev_i32_e32 v7, 31, v6
	v_ashrrev_i32_e32 v9, 31, v8
	v_ashrrev_i32_e32 v3, 31, v2
	v_lshl_add_u64 v[4:5], s[58:59], 0, v[4:5]
	v_lshlrev_b64 v[6:7], 14, v[6:7]
	v_lshlrev_b64 v[8:9], 14, v[8:9]
	v_lshlrev_b64 v[2:3], 14, v[2:3]
	v_lshl_add_u64 v[6:7], s[58:59], 0, v[6:7]
	v_lshl_add_u64 v[8:9], s[58:59], 0, v[8:9]
	v_lshl_add_u64 v[2:3], s[58:59], 0, v[2:3]
	s_nop 0
	s_nop 0
	s_nop 0
	s_nop 0
	v_add_u32_e32 v23, s71, v19
	v_cmp_gt_i32_e64 s[38:39], s10, v23
	s_movk_i32 s3, 0x801
	s_nop 0
	v_cndmask_b32_e64 v0, v19, v23, s[38:39]
	v_ashrrev_i32_e32 v18, 7, v0
	v_lshlrev_b32_e32 v2, 2, v0
	v_ashrrev_i32_e32 v6, 19, v0
	v_cmp_ne_u32_e64 s[54:55], 0, v6
	v_and_b32_e32 v0, 0xfff, v18
	v_and_b32_e32 v20, 0x1fc, v2
	v_sub_u32_e32 v2, 0x1000, v0
	v_cmp_gt_u32_e64 s[40:41], s3, v0
	v_cmp_lt_u32_e64 s[36:37], s68, v0
	v_lshlrev_b32_e32 v30, 9, v6
	v_cndmask_b32_e64 v0, v2, v0, s[40:41]
	v_cmp_ne_u32_e64 s[40:41], s68, v0
	s_and_saveexec_b64 s[12:13], s[40:41]
	s_xor_b64 s[40:41], exec, s[12:13]
	v_mul_i32_i24_e32 v2, 0x900, v6
	v_ashrrev_i32_e32 v3, 31, v2
	v_lshl_add_u64 v[2:3], v[0:1], 0, v[2:3]
	v_lshlrev_b64 v[2:3], 11, v[2:3]
	v_lshl_add_u64 v[2:3], s[50:51], 0, v[2:3]
	v_lshlrev_b32_e32 v4, 2, v20
	v_mov_b32_e32 v5, v1
	v_lshl_add_u64 v[2:3], v[2:3], 0, v[4:5]
	v_lshlrev_b32_e32 v30, 9, v6
	s_andn2_saveexec_b64 s[40:41], s[40:41]
	v_ashrrev_i32_e32 v31, 31, v30
	v_lshl_add_u64 v[2:3], v[30:31], 2, s[60:61]
	v_lshlrev_b32_e32 v4, 2, v20
	v_mov_b32_e32 v5, v1
	v_lshl_add_u64 v[2:3], v[2:3], 0, v[4:5]
	s_or_b64 exec, exec, s[40:41]
	v_and_b32_e32 v4, 0x17ff, v0
	v_or_b32_e32 v38, v30, v20
	v_cmp_ne_u32_e64 s[40:41], 0, v4
	v_ashrrev_i32_e32 v7, 31, v6
	v_lshlrev_b32_e32 v0, 9, v0
	v_or_b32_e32 v32, 1, v38
	v_cndmask_b32_e64 v0, v196, v0, s[40:41]
	v_lshlrev_b64 v[6:7], 22, v[6:7]
	v_ashrrev_i32_e32 v39, 31, v38
	v_ashrrev_i32_e32 v33, 31, v32
	v_lshl_add_u64 v[6:7], s[52:53], 0, v[6:7]
	v_lshlrev_b32_e32 v0, 2, v0
	v_lshlrev_b64 v[30:31], 14, v[38:39]
	v_lshlrev_b64 v[32:33], 14, v[32:33]
	v_lshl_add_u64 v[6:7], v[6:7], 0, v[0:1]
	v_lshlrev_b32_e32 v0, 2, v20
	v_mov_b64_e32 v[26:27], s[48:49]
	v_lshl_add_u64 v[30:31], s[58:59], 0, v[30:31]
	v_lshl_add_u64 v[32:33], s[58:59], 0, v[32:33]
	v_lshl_add_u64 v[6:7], v[6:7], 0, v[0:1]
	v_mad_i64_i32 v[26:27], s[12:13], v18, s75, v[26:27]
	v_lshlrev_b32_e32 v0, 1, v20
	s_nop 0
	v_lshl_add_u64 v[26:27], v[26:27], 0, v[0:1]
	s_nop 0
	v_or_b32_e32 v32, 2, v38
	v_or_b32_e32 v38, 3, v38
	s_mov_b32 s3, 0xad20000
	v_ashrrev_i32_e32 v33, 31, v32
	v_ashrrev_i32_e32 v39, 31, v38
	v_add_co_u32_e64 v26, s[44:45], s3, v26
	v_lshlrev_b64 v[32:33], 14, v[32:33]
	v_lshlrev_b64 v[38:39], 14, v[38:39]
	v_addc_co_u32_e64 v27, s[44:45], 0, v27, s[44:45]
	v_lshl_add_u64 v[32:33], s[58:59], 0, v[32:33]
	v_lshl_add_u64 v[38:39], s[58:59], 0, v[38:39]
	v_mov_b64_e32 v[46:47], v[2:3]
	v_mov_b64_e32 v[48:49], v[6:7]
	v_mov_b64_e32 v[50:51], v[26:27]
	global_load_dwordx4 v[2:5], v[2:3], off
	s_nop 0
	global_load_dwordx4 v[6:9], v[6:7], off
	s_nop 0
	global_load_dwordx2 v[26:27], v[26:27], off offset:1024
	s_mov_b32 s99, 0
	s_cmp_lg_u64 s[26:27], 0
	s_cselect_b32 s98, 0, 0x480000
	v_lshl_add_u64 v[40:41], v[40:41], 0, s[98:99]
	v_lshl_add_u64 v[46:47], v[46:47], 0, s[98:99]
	global_load_dword v52, v[40:41], off
	global_load_dword v53, v[46:47], off
	s_cselect_b32 s98, 0, 0x400000
	v_lshl_add_u64 v[42:43], v[42:43], 0, s[98:99]
	v_lshl_add_u64 v[48:49], v[48:49], 0, s[98:99]
	global_load_dword v54, v[42:43], off
	global_load_dword v55, v[48:49], off
	s_cselect_b32 s98, 0, 0x3400000
	v_lshl_add_u64 v[44:45], v[44:45], 0, s[98:99]
	v_lshl_add_u64 v[50:51], v[50:51], 0, s[98:99]
	global_load_dword v56, v[44:45], off offset:1024
	global_load_dword v57, v[50:51], off offset:1024
	s_nop 0
	s_nop 0
	s_nop 0
	s_nop 0
	s_and_saveexec_b64 s[44:45], s[42:43]
	s_cbranch_execz .LBB0_678
	s_and_saveexec_b64 s[12:13], vcc
	s_xor_b64 s[42:43], exec, s[12:13]
	s_cbranch_execz .LBB0_675
	s_waitcnt vmcnt(6)
	v_pk_add_f32 v[12:13], v[12:13], v[16:17]
	v_pk_add_f32 v[10:11], v[10:11], v[14:15]
.LBB0_675:
	s_andn2_saveexec_b64 s[42:43], s[42:43]
	s_cbranch_execz .LBB0_677
	s_waitcnt vmcnt(6)
	v_sub_f32_e32 v13, v13, v17
	v_sub_f32_e32 v12, v12, v16
	v_sub_f32_e32 v11, v11, v15
	v_sub_f32_e32 v10, v10, v14

; __device__ __forceinline__ unsigned pk2(float lo, float hi) { return f2bf(lo) | (f2bf(hi) << 16); }
; __device__ __forceinline__ float bflo(unsigned u) { return __uint_as_float(u << 16); }
; __device__ __forceinline__ float bfhi(unsigned u) { return __uint_as_float(u & 0xffff0000u); }
; __device__ __forceinline__ float silu_f(float v) { return v / (1.f + __expf(-v)); }
; __device__ __forceinline__ void ph_combine(const Params& p_) {
;     ...
;         for (int u = 0; u < 2; ++u) if (act[u]) { f32x4 s = ce[u];
;             if (use_so[u]) s = (kv[u] <= 2048) ? s - so[u] : s + so[u];
;             const float alt = (kv[u] & 1) ? -1.f : 1.f;
; #pragma unroll
;             for (int j = 0; j < 4; ++j) s[j] += alt * pv[u][j];
;             u32x2 w; w.x = pk2(s[0] * silu_f(bflo(gz[u].x)), s[1] * silu_f(bfhi(gz[u].x))); w.y = pk2(s[2] * silu_f(bflo(gz[u].y)), s[3] * silu_f(bfhi(gz[u].y)));
;             *(u32x2*)(CAT + (size_t)rowv[u] * DM + c4v[u]) = w; }
.LBB0_678:
	s_or_b64 exec, exec, s[44:45]
	s_waitcnt vmcnt(6)
	v_cndmask_b32_e64 v35, v200, v204, s[26:27]
	v_cndmask_b32_e64 v34, v201, v205, s[26:27]
	v_cndmask_b32_e64 v37, v202, v206, s[26:27]
	v_cndmask_b32_e64 v36, v203, v207, s[26:27]
	v_cndmask_b32_e64 v30, v200, v204, s[54:55]
	v_cndmask_b32_e64 v31, v201, v205, s[54:55]
	v_cndmask_b32_e64 v32, v202, v206, s[54:55]
	v_cndmask_b32_e64 v33, v203, v207, s[54:55]
	v_and_b32_e32 v15, 0x80, v19
	v_lshlrev_b32_e32 v0, 16, v35
	v_lshlrev_b32_e32 v14, 16, v37
	v_cmp_eq_u32_e64 s[42:43], 0, v15
	v_lshlrev_b32_e32 v34, 16, v34
	v_lshlrev_b32_e32 v35, 16, v36
	v_lshlrev_b32_e32 v36, 16, v28
	v_cndmask_b32_e64 v15, -v14, v14, s[42:43]
	v_cndmask_b32_e64 v14, -v0, v0, s[42:43]
	v_mov_b32_e32 v16, v10
	v_mov_b32_e32 v17, v12
	v_and_b32_e32 v28, 0xffff0000, v28
	v_pk_add_f32 v[14:15], v[14:15], v[16:17]
	v_cndmask_b32_e64 v17, -v35, v35, s[42:43]
	v_cndmask_b32_e64 v16, -v34, v34, s[42:43]
	v_mov_b32_e32 v12, v11
	v_mul_f32_e32 v0, 0xbfb8aa3b, v36
	v_lshlrev_b32_e32 v19, 16, v29
	v_pk_add_f32 v[10:11], v[16:17], v[12:13]
	v_exp_f32_e32 v12, v0
	v_mul_f32_e32 v0, 0xbfb8aa3b, v28
	v_exp_f32_e32 v16, v0
	v_mul_f32_e32 v0, 0xbfb8aa3b, v19
	v_exp_f32_e32 v13, v0
	v_and_b32_e32 v29, 0xffff0000, v29
	v_ashrrev_i32_e32 v25, 31, v24
	v_pk_add_f32 v[12:13], v[12:13], 1.0 op_sel_hi:[1,0]
	s_nop 0
	v_div_scale_f32 v0, s[12:13], v13, v13, v19
	v_rcp_f32_e32 v17, v0
	s_nop 0
	v_fma_f32 v34, -v0, v17, 1.0
	v_fmac_f32_e32 v17, v34, v17
	v_div_scale_f32 v34, vcc, v19, v13, v19
	v_mul_f32_e32 v35, v34, v17
	v_fma_f32 v37, -v0, v35, v34
	v_fmac_f32_e32 v35, v37, v17
	v_fma_f32 v0, -v0, v35, v34
	v_div_fmas_f32 v0, v0, v17, v35
	v_div_fixup_f32 v13, v0, v13, v19
	v_div_scale_f32 v0, s[12:13], v12, v12, v36
	v_rcp_f32_e32 v17, v0
	s_nop 0
	v_fma_f32 v19, -v0, v17, 1.0
	v_fmac_f32_e32 v17, v19, v17
	v_div_scale_f32 v19, vcc, v36, v12, v36
	v_mul_f32_e32 v34, v19, v17
	v_fma_f32 v35, -v0, v34, v19
	v_fmac_f32_e32 v34, v35, v17
	v_fma_f32 v0, -v0, v34, v19
	v_div_fmas_f32 v0, v0, v17, v34
	v_div_fixup_f32 v12, v0, v12, v36
	v_mul_f32_e32 v0, 0xbfb8aa3b, v29
	v_exp_f32_e32 v17, v0
	v_pk_mul_f32 v[12:13], v[12:13], v[14:15]
	v_pk_add_f32 v[14:15], v[16:17], 1.0 op_sel_hi:[1,0]
	s_nop 0
	v_div_scale_f32 v0, s[12:13], v15, v15, v29
	v_rcp_f32_e32 v16, v0
	s_nop 0
	v_fma_f32 v17, -v0, v16, 1.0
	v_fmac_f32_e32 v16, v17, v16
	v_div_scale_f32 v17, vcc, v29, v15, v29
	v_mul_f32_e32 v19, v17, v16
	v_fma_f32 v34, -v0, v19, v17
	v_fmac_f32_e32 v19, v34, v16
	v_fma_f32 v0, -v0, v19, v17
	v_div_fmas_f32 v0, v0, v16, v19
	v_div_fixup_f32 v15, v0, v15, v29
	v_div_scale_f32 v0, s[12:13], v14, v14, v28
	v_rcp_f32_e32 v16, v0
	s_nop 0
	v_fma_f32 v17, -v0, v16, 1.0
	v_fmac_f32_e32 v16, v17, v16
	v_div_scale_f32 v17, vcc, v28, v14, v28
	v_mul_f32_e32 v19, v17, v16
	v_fma_f32 v29, -v0, v19, v17
	v_fmac_f32_e32 v19, v29, v16
	v_fma_f32 v0, -v0, v19, v17
	v_div_fmas_f32 v0, v0, v16, v19
	v_div_fixup_f32 v14, v0, v14, v28
	v_pk_mul_f32 v[10:11], v[14:15], v[10:11]
	v_and_b32_sdwa v14, v12, v179 dst_sel:DWORD dst_unused:UNUSED_PAD src0_sel:WORD_1 src1_sel:DWORD
	v_and_b32_sdwa v0, v13, v179 dst_sel:DWORD dst_unused:UNUSED_PAD src0_sel:WORD_1 src1_sel:DWORD
	v_add3_u32 v12, v12, v14, s14
	v_and_b32_sdwa v14, v10, v179 dst_sel:DWORD dst_unused:UNUSED_PAD src0_sel:WORD_1 src1_sel:DWORD
	v_add3_u32 v0, v13, v0, s14
	v_and_b32_sdwa v13, v11, v179 dst_sel:DWORD dst_unused:UNUSED_PAD src0_sel:WORD_1 src1_sel:DWORD
	v_add3_u32 v10, v10, v14, s14
	v_add3_u32 v11, v11, v13, s14
	v_and_b32_e32 v10, 0xffff0000, v10
	v_and_b32_e32 v11, 0xffff0000, v11
	v_or_b32_sdwa v10, v10, v12 dst_sel:DWORD dst_unused:UNUSED_PAD src0_sel:DWORD src1_sel:WORD_1
	v_lshlrev_b64 v[12:13], 12, v[24:25]
	v_or_b32_sdwa v11, v11, v0 dst_sel:DWORD dst_unused:UNUSED_PAD src0_sel:DWORD src1_sel:WORD_1
	v_lshl_add_u64 v[12:13], s[56:57], 0, v[12:13]
	v_lshlrev_b32_e32 v0, 1, v22
	v_lshl_add_u64 v[12:13], v[12:13], 0, v[0:1]
	global_store_dwordx2 v[12:13], v[10:11], off offset:3072
	s_and_saveexec_b64 s[44:45], s[38:39]
	s_cbranch_execz .LBB0_663
	s_and_saveexec_b64 s[38:39], s[40:41]
	s_cbranch_execz .LBB0_662
	s_and_saveexec_b64 s[12:13], s[36:37]
	s_xor_b64 s[36:37], exec, s[12:13]
	v_pk_add_f32 v[4:5], v[4:5], v[8:9]
	v_pk_add_f32 v[2:3], v[2:3], v[6:7]
	s_andn2_saveexec_b64 s[36:37], s[36:37]
	s_cbranch_execz .LBB0_661
	v_sub_f32_e32 v5, v5, v9
	v_sub_f32_e32 v4, v4, v8
	v_sub_f32_e32 v3, v3, v7
	v_sub_f32_e32 v2, v2, v6
	s_branch .LBB0_661
